# P0 norm: wave sum of squares by DPP row rotations + permlane swaps instead of six ds_bpermute round trips
# speedup vs baseline: 1.0244x; 1.0013x over previous
; DEV float wsum(float v, int lane) {
; #pragma unroll
;   for (int m = 32; m >= 1; m >>= 1) v += shx(v, m, lane);
;   return v;
; }
; DEV void norm_item(const Params& p, int l, int g, int item, int tid) {
;     ...
;   float4 v[4];
;   float ss = 0.f;
; #pragma unroll
;   for (int i = 0; i < 4; ++i) {
;     v[i] = *(const float4*)(src + i * 256 + lane * 4);
;     ss += v[i].x * v[i].x + v[i].y * v[i].y + v[i].z * v[i].z + v[i].w * v[i].w;
;   }
;   ss = wsum(ss, lane);
;   const float rstd = rsqrtf(ss * (1.f / D) + 1e-6f);
; #pragma unroll
;   for (int i = 0; i < 4; ++i) {
;     int col = i * 256 + lane * 4;
;     float4 gg = *(const float4*)(ng + col);
;     float4 sh = *(const float4*)(md + col);
;     float4 sc = *(const float4*)(md + 1024 + col);
;     uint2 o;
;     o.x = pack2(v[i].x * rstd * gg.x * (1.f + sc.x) + sh.x, v[i].y * rstd * gg.y * (1.f + sc.y) + sh.y);
;     o.y = pack2(v[i].z * rstd * gg.z * (1.f + sc.z) + sh.z, v[i].w * rstd * gg.w * (1.f + sc.w) + sh.w);
;     *(uint2*)(p.u + (long)r * D + col) = o;
;   }
.Lp0_x0:
.Lp0_loop:
	v_mov_b32_e32 v40, v5
	v_mov_b32_e32 v41, v9
	v_mov_b32_e32 v38, v4
	v_mov_b32_e32 v39, v8
	v_mov_b32_e32 v48, v13
	v_mov_b32_e32 v49, v17
	v_pk_mul_f32 v[40:41], v[40:41], v[40:41]
	v_mov_b32_e32 v2, v6
	v_mov_b32_e32 v3, v10
	v_mov_b32_e32 v46, v12
	v_mov_b32_e32 v47, v16
	v_pk_mul_f32 v[48:49], v[48:49], v[48:49]
	v_pk_fma_f32 v[38:39], v[38:39], v[38:39], v[40:41]
	v_mov_b32_e32 v36, v7
	v_mov_b32_e32 v37, v11
	v_mov_b32_e32 v42, v14
	v_mov_b32_e32 v43, v18
	v_pk_fma_f32 v[40:41], v[46:47], v[46:47], v[48:49]
	v_pk_fma_f32 v[2:3], v[2:3], v[2:3], v[38:39]
	v_mov_b32_e32 v44, v15
	v_mov_b32_e32 v45, v19
	v_pk_fma_f32 v[38:39], v[42:43], v[42:43], v[40:41]
	v_pk_fma_f32 v[2:3], v[36:37], v[36:37], v[2:3]
	v_pk_fma_f32 v[36:37], v[44:45], v[44:45], v[38:39]
	v_add_f32_e32 v2, v2, v3
	v_add_f32_e32 v2, v2, v36
	v_add_f32_e32 v2, v2, v37
	s_nop 1
	v_add_f32_dpp v2, v2, v2 row_ror:8 row_mask:0xf bank_mask:0xf
	s_nop 1
	v_add_f32_dpp v2, v2, v2 row_ror:4 row_mask:0xf bank_mask:0xf
	s_nop 1
	v_add_f32_dpp v2, v2, v2 row_ror:2 row_mask:0xf bank_mask:0xf
	s_nop 1
	v_add_f32_dpp v2, v2, v2 row_ror:1 row_mask:0xf bank_mask:0xf
	v_mov_b32_e32 v1, v2
	s_nop 1
	v_permlane16_swap_b32_e32 v2, v1
	s_nop 1
	v_add_f32_e32 v2, v2, v1
	v_mov_b32_e32 v1, v2
	s_nop 1
	v_permlane32_swap_b32_e32 v2, v1
	s_nop 1
	v_add_f32_e32 v0, v2, v1
	v_fmamk_f32 v0, v0, 0x3a800000, v196
	v_mul_f32_e32 v1, 0x4b800000, v0
	v_cmp_gt_f32_e32 vcc, s46, v0
	s_nop 1
	v_cndmask_b32_e32 v0, v0, v1, vcc
	v_rsq_f32_e32 v40, v0
	s_nop 0
	v_mul_f32_e32 v20, 0x45800000, v40
	v_cndmask_b32_e32 v40, v40, v20, vcc
	v_pk_add_f32 v[22:23], v[202:203], 1.0 op_sel_hi:[1,0]
	v_pk_add_f32 v[20:21], v[200:201], 1.0 op_sel_hi:[1,0]
	v_pk_mul_f32 v[24:25], v[4:5], v[40:41] op_sel_hi:[1,0]
	v_pk_mul_f32 v[26:27], v[6:7], v[40:41] op_sel_hi:[1,0]
	v_pk_mul_f32 v[24:25], v[96:97], v[24:25]
	v_pk_mul_f32 v[26:27], v[98:99], v[26:27]
	v_pk_fma_f32 v[20:21], v[20:21], v[24:25], v[174:175]
	v_pk_fma_f32 v[22:23], v[22:23], v[26:27], v[176:177]
	v_cvt_pk_bf16_f32 v70, v20, v21
	v_cvt_pk_bf16_f32 v71, v22, v23
	global_store_dwordx2 v50, v[70:71], s[12:13]
	v_pk_mul_f32 v[24:25], v[8:9], v[40:41] op_sel_hi:[1,0]
	v_pk_mul_f32 v[26:27], v[10:11], v[40:41] op_sel_hi:[1,0]
	v_pk_mul_f32 v[24:25], v[24:25], v[100:101]
	v_pk_mul_f32 v[26:27], v[26:27], v[102:103]
	v_pk_add_f32 v[20:21], v[204:205], 1.0 op_sel_hi:[1,0]
	v_pk_add_f32 v[22:23], v[206:207], 1.0 op_sel_hi:[1,0]
	v_pk_fma_f32 v[20:21], v[24:25], v[20:21], v[178:179]
	v_pk_fma_f32 v[22:23], v[26:27], v[22:23], v[180:181]
	v_cvt_pk_bf16_f32 v72, v20, v21
	v_cvt_pk_bf16_f32 v73, v22, v23
	global_store_dwordx2 v50, v[72:73], s[12:13] offset:512
	v_pk_mul_f32 v[24:25], v[12:13], v[40:41] op_sel_hi:[1,0]
	v_pk_mul_f32 v[26:27], v[14:15], v[40:41] op_sel_hi:[1,0]
	v_pk_mul_f32 v[24:25], v[24:25], v[104:105]
	v_pk_mul_f32 v[26:27], v[26:27], v[106:107]
	v_pk_add_f32 v[20:21], v[208:209], 1.0 op_sel_hi:[1,0]
	v_pk_add_f32 v[22:23], v[210:211], 1.0 op_sel_hi:[1,0]
	v_pk_fma_f32 v[20:21], v[24:25], v[20:21], v[182:183]
	v_pk_fma_f32 v[22:23], v[26:27], v[22:23], v[184:185]
	v_cvt_pk_bf16_f32 v74, v20, v21
	v_cvt_pk_bf16_f32 v75, v22, v23
	global_store_dwordx2 v50, v[74:75], s[12:13] offset:1024
	v_pk_mul_f32 v[24:25], v[16:17], v[40:41] op_sel_hi:[1,0]
	v_pk_mul_f32 v[26:27], v[18:19], v[40:41] op_sel_hi:[1,0]
	v_pk_mul_f32 v[24:25], v[24:25], v[108:109]
	v_pk_mul_f32 v[26:27], v[26:27], v[110:111]
	v_pk_add_f32 v[20:21], v[212:213], 1.0 op_sel_hi:[1,0]
	v_pk_add_f32 v[22:23], v[214:215], 1.0 op_sel_hi:[1,0]
	v_pk_fma_f32 v[20:21], v[24:25], v[20:21], v[186:187]
	v_pk_fma_f32 v[22:23], v[26:27], v[22:23], v[188:189]
	v_cvt_pk_bf16_f32 v76, v20, v21
	v_cvt_pk_bf16_f32 v77, v22, v23
	global_store_dwordx2 v50, v[76:77], s[12:13] offset:1536
	s_cmp_lg_u32 s45, 0
	s_cbranch_scc0 .Lp0_done
	s_mov_b32 s44, 0
	s_cmp_ge_u32 s18, s47
	s_cbranch_scc1 .Lp0_skipA_2
	s_mov_b32 s44, 1
	s_add_i32 s19, s15, s60
	s_mul_hi_u32 s32, s19, 0x38e38e39
	s_lshr_b32 s32, s32, 9
	s_mul_i32 s11, s32, 0x900
	s_sub_i32 s61, s19, s11
	s_lshl_b32 s12, s19, 11
	s_add_u32 s12, s86, s12
	s_addc_u32 s13, s87, 0
	v_readlane_b32 s19, v255, 29
	s_nop 0
	s_add_i32 s32, s32, s19
	s_add_i32 s19, s61, 0xffffff00
	s_cmp_lt_u32 s61, 0x100
	s_cselect_b32 s62, s58, s48
	s_cselect_b32 s63, s59, s49
	s_cselect_b32 s11, 20, 23
	s_cselect_b32 s79, 32, s32
	s_cselect_b32 s19, s61, s19
	s_lshl_b32 s32, s32, s11
	s_lshl_b32 s19, s19, 12
	s_add_u32 s32, s32, s19
	s_add_u32 s62, s62, s32
	s_addc_u32 s63, s63, 0
	s_add_i32 s79, s79, s10
	s_mul_i32 s79, s79, 0x3000
	v_readlane_b32 s19, v253, 21
	v_readlane_b32 s32, v253, 22
	s_nop 0
	s_add_u32 s6, s19, s79
	s_addc_u32 s7, s32, 0
	s_add_u32 s8, s6, 0x1000
	s_addc_u32 s9, s7, 0
	global_load_dwordx4 v[4:7], v156, s[62:63]
	global_load_dwordx4 v[8:11], v156, s[62:63] offset:1024
	global_load_dwordx4 v[12:15], v156, s[62:63] offset:2048
	global_load_dwordx4 v[16:19], v156, s[62:63] offset:3072
	s_cmp_eq_u32 s6, s98
	s_cbranch_scc1 .Lp0_skipA_2_same
	s_mov_b32 s98, s6
	global_load_dwordx4 v[200:203], v156, s[8:9]
	global_load_dwordx4 v[174:177], v156, s[6:7]
	global_load_dwordx4 v[204:207], v156, s[8:9] offset:1024
	global_load_dwordx4 v[178:181], v156, s[6:7] offset:1024
	global_load_dwordx4 v[208:211], v156, s[8:9] offset:2048
	global_load_dwordx4 v[182:185], v156, s[6:7] offset:2048
	global_load_dwordx4 v[212:215], v156, s[8:9] offset:3072
	global_load_dwordx4 v[186:189], v156, s[6:7] offset:3072

; DEV float wsum(float v, int lane) {
; #pragma unroll
;   for (int m = 32; m >= 1; m >>= 1) v += shx(v, m, lane);
;   return v;
; }
; DEV void norm_item(const Params& p, int l, int g, int item, int tid) {
;     ...
;   float4 v[4];
;   float ss = 0.f;
; #pragma unroll
;   for (int i = 0; i < 4; ++i) {
;     v[i] = *(const float4*)(src + i * 256 + lane * 4);
;     ss += v[i].x * v[i].x + v[i].y * v[i].y + v[i].z * v[i].z + v[i].w * v[i].w;
;   }
;   ss = wsum(ss, lane);
;   const float rstd = rsqrtf(ss * (1.f / D) + 1e-6f);
; #pragma unroll
;   for (int i = 0; i < 4; ++i) {
;     int col = i * 256 + lane * 4;
;     float4 gg = *(const float4*)(ng + col);
;     float4 sh = *(const float4*)(md + col);
;     float4 sc = *(const float4*)(md + 1024 + col);
;     uint2 o;
;     o.x = pack2(v[i].x * rstd * gg.x * (1.f + sc.x) + sh.x, v[i].y * rstd * gg.y * (1.f + sc.y) + sh.y);
;     o.y = pack2(v[i].z * rstd * gg.z * (1.f + sc.z) + sh.z, v[i].w * rstd * gg.w * (1.f + sc.w) + sh.w);
;     *(uint2*)(p.u + (long)r * D + col) = o;
;   }
.Lp0_x1:
	v_mov_b32_e32 v40, v137
	v_mov_b32_e32 v41, v141
	v_mov_b32_e32 v38, v136
	v_mov_b32_e32 v39, v140
	v_mov_b32_e32 v48, v145
	v_mov_b32_e32 v49, v149
	v_pk_mul_f32 v[40:41], v[40:41], v[40:41]
	v_mov_b32_e32 v2, v138
	v_mov_b32_e32 v3, v142
	v_mov_b32_e32 v46, v144
	v_mov_b32_e32 v47, v148
	v_pk_mul_f32 v[48:49], v[48:49], v[48:49]
	v_pk_fma_f32 v[38:39], v[38:39], v[38:39], v[40:41]
	v_mov_b32_e32 v36, v139
	v_mov_b32_e32 v37, v143
	v_mov_b32_e32 v42, v146
	v_mov_b32_e32 v43, v150
	v_pk_fma_f32 v[40:41], v[46:47], v[46:47], v[48:49]
	v_pk_fma_f32 v[2:3], v[2:3], v[2:3], v[38:39]
	v_mov_b32_e32 v44, v147
	v_mov_b32_e32 v45, v151
	v_pk_fma_f32 v[38:39], v[42:43], v[42:43], v[40:41]
	v_pk_fma_f32 v[2:3], v[36:37], v[36:37], v[2:3]
	v_pk_fma_f32 v[36:37], v[44:45], v[44:45], v[38:39]
	v_add_f32_e32 v2, v2, v3
	v_add_f32_e32 v2, v2, v36
	v_add_f32_e32 v2, v2, v37
	s_nop 1
	v_add_f32_dpp v2, v2, v2 row_ror:8 row_mask:0xf bank_mask:0xf
	s_nop 1
	v_add_f32_dpp v2, v2, v2 row_ror:4 row_mask:0xf bank_mask:0xf
	s_nop 1
	v_add_f32_dpp v2, v2, v2 row_ror:2 row_mask:0xf bank_mask:0xf
	s_nop 1
	v_add_f32_dpp v2, v2, v2 row_ror:1 row_mask:0xf bank_mask:0xf
	v_mov_b32_e32 v1, v2
	s_nop 1
	v_permlane16_swap_b32_e32 v2, v1
	s_nop 1
	v_add_f32_e32 v2, v2, v1
	v_mov_b32_e32 v1, v2
	s_nop 1
	v_permlane32_swap_b32_e32 v2, v1
	s_nop 1
	v_add_f32_e32 v0, v2, v1
	v_fmamk_f32 v0, v0, 0x3a800000, v196
	v_mul_f32_e32 v1, 0x4b800000, v0
	v_cmp_gt_f32_e32 vcc, s46, v0
	s_nop 1
	v_cndmask_b32_e32 v0, v0, v1, vcc
	v_rsq_f32_e32 v40, v0
	s_nop 0
	v_mul_f32_e32 v20, 0x45800000, v40
	v_cndmask_b32_e32 v40, v40, v20, vcc
	v_pk_add_f32 v[22:23], v[218:219], 1.0 op_sel_hi:[1,0]
	v_pk_add_f32 v[20:21], v[216:217], 1.0 op_sel_hi:[1,0]
	v_pk_mul_f32 v[24:25], v[136:137], v[40:41] op_sel_hi:[1,0]
	v_pk_mul_f32 v[26:27], v[138:139], v[40:41] op_sel_hi:[1,0]
	v_pk_mul_f32 v[24:25], v[96:97], v[24:25]
	v_pk_mul_f32 v[26:27], v[98:99], v[26:27]
	v_pk_fma_f32 v[20:21], v[20:21], v[24:25], v[158:159]
	v_pk_fma_f32 v[22:23], v[22:23], v[26:27], v[160:161]
	v_cvt_pk_bf16_f32 v70, v20, v21
	v_cvt_pk_bf16_f32 v71, v22, v23
	global_store_dwordx2 v50, v[70:71], s[54:55]
	v_pk_mul_f32 v[24:25], v[140:141], v[40:41] op_sel_hi:[1,0]
	v_pk_mul_f32 v[26:27], v[142:143], v[40:41] op_sel_hi:[1,0]
	v_pk_mul_f32 v[24:25], v[24:25], v[100:101]
	v_pk_mul_f32 v[26:27], v[26:27], v[102:103]
	v_pk_add_f32 v[20:21], v[220:221], 1.0 op_sel_hi:[1,0]
	v_pk_add_f32 v[22:23], v[222:223], 1.0 op_sel_hi:[1,0]
	v_pk_fma_f32 v[20:21], v[24:25], v[20:21], v[162:163]
	v_pk_fma_f32 v[22:23], v[26:27], v[22:23], v[164:165]
	v_cvt_pk_bf16_f32 v72, v20, v21
	v_cvt_pk_bf16_f32 v73, v22, v23
	global_store_dwordx2 v50, v[72:73], s[54:55] offset:512
	v_pk_mul_f32 v[24:25], v[144:145], v[40:41] op_sel_hi:[1,0]
	v_pk_mul_f32 v[26:27], v[146:147], v[40:41] op_sel_hi:[1,0]
	v_pk_mul_f32 v[24:25], v[24:25], v[104:105]
	v_pk_mul_f32 v[26:27], v[26:27], v[106:107]
	v_pk_add_f32 v[20:21], v[224:225], 1.0 op_sel_hi:[1,0]
	v_pk_add_f32 v[22:23], v[226:227], 1.0 op_sel_hi:[1,0]
	v_pk_fma_f32 v[20:21], v[24:25], v[20:21], v[166:167]
	v_pk_fma_f32 v[22:23], v[26:27], v[22:23], v[168:169]
	v_cvt_pk_bf16_f32 v74, v20, v21
	v_cvt_pk_bf16_f32 v75, v22, v23
	global_store_dwordx2 v50, v[74:75], s[54:55] offset:1024
	v_pk_mul_f32 v[24:25], v[148:149], v[40:41] op_sel_hi:[1,0]
	v_pk_mul_f32 v[26:27], v[150:151], v[40:41] op_sel_hi:[1,0]
	v_pk_mul_f32 v[24:25], v[24:25], v[108:109]
	v_pk_mul_f32 v[26:27], v[26:27], v[110:111]
	v_pk_add_f32 v[20:21], v[228:229], 1.0 op_sel_hi:[1,0]
	v_pk_add_f32 v[22:23], v[230:231], 1.0 op_sel_hi:[1,0]
	v_pk_fma_f32 v[20:21], v[24:25], v[20:21], v[170:171]
	v_pk_fma_f32 v[22:23], v[26:27], v[22:23], v[172:173]
	v_cvt_pk_bf16_f32 v76, v20, v21
	v_cvt_pk_bf16_f32 v77, v22, v23
	global_store_dwordx2 v50, v[76:77], s[54:55] offset:1536
	s_cmp_lg_u32 s44, 0
	s_cbranch_scc0 .Lp0_done
	s_mov_b32 s45, 0
	s_cmp_ge_u32 s18, s47
	s_cbranch_scc1 .Lp0_skipB_3
	s_mov_b32 s45, 1
	s_add_i32 s19, s15, s60
	s_mul_hi_u32 s32, s19, 0x38e38e39
	s_lshr_b32 s32, s32, 9
	s_mul_i32 s11, s32, 0x900
	s_sub_i32 s61, s19, s11
	s_lshl_b32 s54, s19, 11
	s_add_u32 s54, s86, s54
	s_addc_u32 s55, s87, 0
	v_readlane_b32 s19, v255, 29
	s_nop 0
	s_add_i32 s32, s32, s19
	s_add_i32 s19, s61, 0xffffff00
	s_cmp_lt_u32 s61, 0x100
	s_cselect_b32 s56, s58, s48
	s_cselect_b32 s57, s59, s49
	s_cselect_b32 s11, 20, 23
	s_cselect_b32 s79, 32, s32
	s_cselect_b32 s19, s61, s19
	s_lshl_b32 s32, s32, s11
	s_lshl_b32 s19, s19, 12
	s_add_u32 s32, s32, s19
	s_add_u32 s56, s56, s32
	s_addc_u32 s57, s57, 0
	s_add_i32 s79, s79, s10
	s_mul_i32 s79, s79, 0x3000
	v_readlane_b32 s19, v253, 21
	v_readlane_b32 s32, v253, 22
	s_nop 0
	s_add_u32 s50, s19, s79
	s_addc_u32 s51, s32, 0
	s_add_u32 s52, s50, 0x1000
	s_addc_u32 s53, s51, 0
	global_load_dwordx4 v[136:139], v156, s[56:57]
	global_load_dwordx4 v[140:143], v156, s[56:57] offset:1024
	global_load_dwordx4 v[144:147], v156, s[56:57] offset:2048
	global_load_dwordx4 v[148:151], v156, s[56:57] offset:3072
	s_cmp_eq_u32 s50, s99
	s_cbranch_scc1 .Lp0_skipB_3_same
	s_mov_b32 s99, s50
	global_load_dwordx4 v[216:219], v156, s[52:53]
	global_load_dwordx4 v[158:161], v156, s[50:51]
	global_load_dwordx4 v[220:223], v156, s[52:53] offset:1024
	global_load_dwordx4 v[162:165], v156, s[50:51] offset:1024
	global_load_dwordx4 v[224:227], v156, s[52:53] offset:2048
	global_load_dwordx4 v[166:169], v156, s[50:51] offset:2048
	global_load_dwordx4 v[228:231], v156, s[52:53] offset:3072
	global_load_dwordx4 v[170:173], v156, s[50:51] offset:3072
